# neighbourhood attention: the per-head bias table is reloaded only for a virtual block's first unit and when the head changes, instead of two serialized global round trips per unit
# speedup vs baseline: 1.0027x; 1.0027x over previous
.LBB0_326:
	s_cmp_eq_u32 s91, 0
	s_cselect_b64 s[34:35], -1, 0
	s_cmp_lg_u32 s91, 0
	s_waitcnt lgkmcnt(0)
	s_barrier
	s_waitcnt vmcnt(0)
	ds_write_b128 v127, v[4:7] offset:9216
	ds_write_b128 v127, v[8:11] offset:13824
	ds_write_b128 v127, v[12:15] offset:18432
	ds_write_b128 v127, v[16:19] offset:23040
	ds_write_b128 v130, v[20:23] offset:27648
	ds_write_b128 v130, v[24:27] offset:32000
	ds_write_b128 v130, v[28:31] offset:36352
	ds_write_b128 v130, v[32:35] offset:40704
	s_cbranch_scc1 .LBB0_330
	ds_write_b128 v127, v[44:47]
	ds_write_b128 v127, v[48:51] offset:4608
	v_readfirstlane_b32 s56, v152
	s_nop 0
	s_and_b32 s56, s56, 62
	s_cmp_eq_u32 s90, 0
	s_cselect_b32 s56, 0, s56
	s_cmp_lg_u32 s56, 0
	s_cbranch_scc1 .LBB0_330
	v_mov_b32_e32 v0, s84
	ds_read_b64 v[2:3], v0
	s_mov_b64 s[56:57], 0
	v_mov_b32_e32 v0, v150
	v_mov_b32_e32 v68, v149
	s_waitcnt lgkmcnt(0)
	v_add_co_u32_e32 v2, vcc, v2, v118
	v_addc_co_u32_e32 v3, vcc, v3, v119, vcc

.LBB0_410:
	s_cmp_eq_u32 s83, 0
	s_cselect_b64 s[34:35], -1, 0
	s_cmp_lg_u32 s83, 0
	s_waitcnt lgkmcnt(0)
	s_barrier
	s_waitcnt vmcnt(0)
	ds_write_b128 v124, v[4:7] offset:9216
	ds_write_b128 v124, v[8:11] offset:13824
	ds_write_b128 v124, v[12:15] offset:18432
	ds_write_b128 v124, v[16:19] offset:23040
	ds_write_b128 v159, v[20:23] offset:27648
	ds_write_b128 v159, v[24:27] offset:32000
	ds_write_b128 v159, v[28:31] offset:36352
	ds_write_b128 v159, v[32:35] offset:40704
	s_cbranch_scc1 .LBB0_414
	ds_write_b128 v124, v[44:47]
	ds_write_b128 v124, v[48:51] offset:4608
	v_readfirstlane_b32 s56, v148
	s_nop 0
	s_and_b32 s56, s56, 62
	s_cmp_eq_u32 s82, 0
	s_cselect_b32 s56, 0, s56
	s_cmp_lg_u32 s56, 0
	s_cbranch_scc1 .LBB0_414
	v_mov_b32_e32 v0, s76
	ds_read_b64 v[2:3], v0
	s_mov_b64 s[56:57], 0
	v_mov_b32_e32 v0, v146
	v_mov_b32_e32 v68, v145
	s_waitcnt lgkmcnt(0)
	v_add_co_u32_e32 v2, vcc, v2, v116
	v_addc_co_u32_e32 v3, vcc, v3, v117, vcc
